# combo6 + S5 scan loops: 56 broadcast v_mov removed by reading the high half via op_sel (bit-identical)
# speedup vs baseline: 1.0146x; 1.0129x over previous
.LBB0_208:
	s_add_i32 s12, s10, s11
	v_mov_b32_e32 v17, s12
	ds_read_b128 v[26:29], v17
	ds_read_b128 v[30:33], v17 offset:16
	ds_read_b128 v[38:41], v17 offset:32
	ds_read_b128 v[92:95], v17 offset:48
	s_addk_i32 s11, 0x200
	s_waitcnt lgkmcnt(0)
	v_pk_fma_f32 v[18:19], v[26:27], v[82:83], 0 op_sel_hi:[0,1,0]
	s_waitcnt lgkmcnt(2)
	v_pk_fma_f32 v[22:23], v[30:31], v[64:65], 0 op_sel_hi:[0,1,0]
	s_waitcnt lgkmcnt(1)
	v_pk_fma_f32 v[18:19], v[38:39], v[56:57], v[18:19] op_sel_hi:[0,1,1]
	s_waitcnt lgkmcnt(0)
	v_pk_fma_f32 v[22:23], v[92:93], v[48:49], v[22:23] op_sel_hi:[0,1,1]
	v_pk_fma_f32 v[18:19], v[26:27], v[62:63], v[18:19] op_sel:[1,0,0]
	v_pk_fma_f32 v[22:23], v[30:31], v[50:51], v[22:23] op_sel:[1,0,0]
	v_pk_fma_f32 v[18:19], v[38:39], v[42:43], v[18:19] op_sel:[1,0,0]
	v_pk_fma_f32 v[22:23], v[92:93], v[34:35], v[22:23] op_sel:[1,0,0]
	v_pk_fma_f32 v[18:19], v[28:29], v[58:59], v[18:19] op_sel_hi:[0,1,1]
	v_pk_fma_f32 v[22:23], v[32:33], v[54:55], v[22:23] op_sel_hi:[0,1,1]
	v_pk_fma_f32 v[18:19], v[40:41], v[46:47], v[18:19] op_sel_hi:[0,1,1]
	v_pk_fma_f32 v[22:23], v[94:95], v[84:85], v[22:23] op_sel_hi:[0,1,1]
	v_pk_fma_f32 v[18:19], v[28:29], v[60:61], v[18:19] op_sel:[1,0,0]
	v_pk_fma_f32 v[22:23], v[32:33], v[52:53], v[22:23] op_sel:[1,0,0]
	v_pk_fma_f32 v[18:19], v[40:41], v[44:45], v[18:19] op_sel:[1,0,0]
	v_pk_fma_f32 v[22:23], v[94:95], v[36:37], v[22:23] op_sel:[1,0,0]
	v_pk_mul_f32 v[26:27], v[80:81], v[76:77] op_sel:[0,1] op_sel_hi:[1,0]
	v_pk_add_f32 v[18:19], v[18:19], v[22:23]
	v_pk_fma_f32 v[22:23], v[78:79], v[76:77], v[26:27] neg_lo:[0,0,1] neg_hi:[0,0,1]
	v_pk_fma_f32 v[26:27], v[78:79], v[76:77], v[26:27]
	s_cmpk_eq_i32 s11, 0x400
	v_mov_b32_e32 v23, v27
	v_pk_add_f32 v[18:19], v[22:23], v[18:19]
	s_nop 0
	v_cvt_pk_bf16_f32 v22, v18, s0
	ds_write_b16 v16, v22
	v_cvt_pk_bf16_f32 v22, v19, s0
	ds_write_b16 v16, v22 offset:128
	ds_read_b128 v[26:29], v17 offset:64
	ds_read_b128 v[30:33], v17 offset:80
	ds_read_b128 v[38:41], v17 offset:96
	ds_read_b128 v[92:95], v17 offset:112
	s_waitcnt lgkmcnt(0)
	v_pk_fma_f32 v[22:23], v[26:27], v[82:83], 0 op_sel_hi:[0,1,0]
	s_waitcnt lgkmcnt(2)
	v_pk_fma_f32 v[76:77], v[30:31], v[64:65], 0 op_sel_hi:[0,1,0]
	s_waitcnt lgkmcnt(1)
	v_pk_fma_f32 v[22:23], v[38:39], v[56:57], v[22:23] op_sel_hi:[0,1,1]
	s_waitcnt lgkmcnt(0)
	v_pk_fma_f32 v[76:77], v[92:93], v[48:49], v[76:77] op_sel_hi:[0,1,1]
	v_pk_fma_f32 v[22:23], v[26:27], v[62:63], v[22:23] op_sel:[1,0,0]
	v_pk_fma_f32 v[26:27], v[30:31], v[50:51], v[76:77] op_sel:[1,0,0]
	v_pk_fma_f32 v[22:23], v[38:39], v[42:43], v[22:23] op_sel:[1,0,0]
	v_pk_fma_f32 v[26:27], v[92:93], v[34:35], v[26:27] op_sel:[1,0,0]
	v_pk_fma_f32 v[22:23], v[28:29], v[58:59], v[22:23] op_sel_hi:[0,1,1]
	v_pk_fma_f32 v[26:27], v[32:33], v[54:55], v[26:27] op_sel_hi:[0,1,1]
	v_pk_fma_f32 v[22:23], v[40:41], v[46:47], v[22:23] op_sel_hi:[0,1,1]
	v_pk_fma_f32 v[26:27], v[94:95], v[84:85], v[26:27] op_sel_hi:[0,1,1]
	v_pk_fma_f32 v[22:23], v[28:29], v[60:61], v[22:23] op_sel:[1,0,0]
	v_pk_fma_f32 v[26:27], v[32:33], v[52:53], v[26:27] op_sel:[1,0,0]
	v_pk_fma_f32 v[22:23], v[40:41], v[44:45], v[22:23] op_sel:[1,0,0]
	v_pk_fma_f32 v[26:27], v[94:95], v[36:37], v[26:27] op_sel:[1,0,0]
	v_pk_mul_f32 v[28:29], v[80:81], v[18:19] op_sel:[0,1] op_sel_hi:[1,0]
	v_pk_add_f32 v[22:23], v[22:23], v[26:27]
	v_pk_fma_f32 v[26:27], v[78:79], v[18:19], v[28:29] neg_lo:[0,0,1] neg_hi:[0,0,1]
	v_pk_fma_f32 v[18:19], v[78:79], v[18:19], v[28:29]
	s_nop 0
	v_mov_b32_e32 v27, v19
	v_pk_add_f32 v[18:19], v[26:27], v[22:23]
	s_nop 0
	v_cvt_pk_bf16_f32 v22, v18, s0
	ds_write_b16 v16, v22 offset:272
	v_cvt_pk_bf16_f32 v22, v19, s0
	ds_write_b16 v16, v22 offset:400
	ds_read_b128 v[26:29], v17 offset:128
	ds_read_b128 v[30:33], v17 offset:144
	ds_read_b128 v[38:41], v17 offset:160
	ds_read_b128 v[92:95], v17 offset:176
	s_waitcnt lgkmcnt(0)
	v_pk_fma_f32 v[22:23], v[26:27], v[82:83], 0 op_sel_hi:[0,1,0]
	s_waitcnt lgkmcnt(2)
	v_pk_fma_f32 v[76:77], v[30:31], v[64:65], 0 op_sel_hi:[0,1,0]
	s_waitcnt lgkmcnt(1)
	v_pk_fma_f32 v[22:23], v[38:39], v[56:57], v[22:23] op_sel_hi:[0,1,1]
	s_waitcnt lgkmcnt(0)
	v_pk_fma_f32 v[76:77], v[92:93], v[48:49], v[76:77] op_sel_hi:[0,1,1]
	v_pk_fma_f32 v[22:23], v[26:27], v[62:63], v[22:23] op_sel:[1,0,0]
	v_pk_fma_f32 v[26:27], v[30:31], v[50:51], v[76:77] op_sel:[1,0,0]
	v_pk_fma_f32 v[22:23], v[38:39], v[42:43], v[22:23] op_sel:[1,0,0]
	v_pk_fma_f32 v[26:27], v[92:93], v[34:35], v[26:27] op_sel:[1,0,0]
	v_pk_fma_f32 v[22:23], v[28:29], v[58:59], v[22:23] op_sel_hi:[0,1,1]
	v_pk_fma_f32 v[26:27], v[32:33], v[54:55], v[26:27] op_sel_hi:[0,1,1]
	v_pk_fma_f32 v[22:23], v[40:41], v[46:47], v[22:23] op_sel_hi:[0,1,1]
	v_pk_fma_f32 v[26:27], v[94:95], v[84:85], v[26:27] op_sel_hi:[0,1,1]
	v_pk_fma_f32 v[22:23], v[28:29], v[60:61], v[22:23] op_sel:[1,0,0]
	v_pk_fma_f32 v[26:27], v[32:33], v[52:53], v[26:27] op_sel:[1,0,0]
	v_pk_fma_f32 v[22:23], v[40:41], v[44:45], v[22:23] op_sel:[1,0,0]
	v_pk_fma_f32 v[26:27], v[94:95], v[36:37], v[26:27] op_sel:[1,0,0]
	v_pk_mul_f32 v[28:29], v[80:81], v[18:19] op_sel:[0,1] op_sel_hi:[1,0]
	v_pk_add_f32 v[22:23], v[22:23], v[26:27]
	v_pk_fma_f32 v[26:27], v[78:79], v[18:19], v[28:29] neg_lo:[0,0,1] neg_hi:[0,0,1]
	v_pk_fma_f32 v[18:19], v[78:79], v[18:19], v[28:29]
	s_nop 0
	v_mov_b32_e32 v27, v19
	v_pk_add_f32 v[18:19], v[26:27], v[22:23]
	s_nop 0
	v_cvt_pk_bf16_f32 v22, v18, s0
	ds_write_b16 v16, v22 offset:544
	v_cvt_pk_bf16_f32 v22, v19, s0
	ds_write_b16 v16, v22 offset:672
	ds_read_b128 v[26:29], v17 offset:192
	ds_read_b128 v[30:33], v17 offset:208
	ds_read_b128 v[38:41], v17 offset:224
	ds_read_b128 v[92:95], v17 offset:240
	s_waitcnt lgkmcnt(0)
	v_pk_fma_f32 v[22:23], v[26:27], v[82:83], 0 op_sel_hi:[0,1,0]
	s_waitcnt lgkmcnt(2)
	v_pk_fma_f32 v[76:77], v[30:31], v[64:65], 0 op_sel_hi:[0,1,0]
	s_waitcnt lgkmcnt(1)
	v_pk_fma_f32 v[22:23], v[38:39], v[56:57], v[22:23] op_sel_hi:[0,1,1]
	s_waitcnt lgkmcnt(0)
	v_pk_fma_f32 v[76:77], v[92:93], v[48:49], v[76:77] op_sel_hi:[0,1,1]
	v_pk_fma_f32 v[22:23], v[26:27], v[62:63], v[22:23] op_sel:[1,0,0]
	v_pk_fma_f32 v[26:27], v[30:31], v[50:51], v[76:77] op_sel:[1,0,0]
	v_pk_fma_f32 v[22:23], v[38:39], v[42:43], v[22:23] op_sel:[1,0,0]
	v_pk_fma_f32 v[26:27], v[92:93], v[34:35], v[26:27] op_sel:[1,0,0]
	v_pk_fma_f32 v[22:23], v[28:29], v[58:59], v[22:23] op_sel_hi:[0,1,1]
	v_pk_fma_f32 v[26:27], v[32:33], v[54:55], v[26:27] op_sel_hi:[0,1,1]
	v_pk_fma_f32 v[22:23], v[40:41], v[46:47], v[22:23] op_sel_hi:[0,1,1]
	v_pk_fma_f32 v[26:27], v[94:95], v[84:85], v[26:27] op_sel_hi:[0,1,1]
	v_pk_fma_f32 v[22:23], v[28:29], v[60:61], v[22:23] op_sel:[1,0,0]
	v_pk_fma_f32 v[26:27], v[32:33], v[52:53], v[26:27] op_sel:[1,0,0]
	v_pk_fma_f32 v[22:23], v[40:41], v[44:45], v[22:23] op_sel:[1,0,0]
	v_pk_fma_f32 v[26:27], v[94:95], v[36:37], v[26:27] op_sel:[1,0,0]
	v_pk_mul_f32 v[28:29], v[80:81], v[18:19] op_sel:[0,1] op_sel_hi:[1,0]
	v_pk_add_f32 v[22:23], v[22:23], v[26:27]
	v_pk_fma_f32 v[26:27], v[78:79], v[18:19], v[28:29] neg_lo:[0,0,1] neg_hi:[0,0,1]
	v_pk_fma_f32 v[18:19], v[78:79], v[18:19], v[28:29]
	s_nop 0
	v_mov_b32_e32 v27, v19
	v_pk_add_f32 v[18:19], v[26:27], v[22:23]
	s_nop 0
	v_cvt_pk_bf16_f32 v22, v18, s0
	ds_write_b16 v16, v22 offset:816
	v_cvt_pk_bf16_f32 v22, v19, s0
	ds_write_b16 v16, v22 offset:944
	ds_read_b128 v[26:29], v17 offset:256
	ds_read_b128 v[30:33], v17 offset:272
	ds_read_b128 v[38:41], v17 offset:288
	ds_read_b128 v[92:95], v17 offset:304
	s_waitcnt lgkmcnt(0)
	v_pk_fma_f32 v[22:23], v[26:27], v[82:83], 0 op_sel_hi:[0,1,0]
	s_waitcnt lgkmcnt(2)
	v_pk_fma_f32 v[76:77], v[30:31], v[64:65], 0 op_sel_hi:[0,1,0]
	s_waitcnt lgkmcnt(1)
	v_pk_fma_f32 v[22:23], v[38:39], v[56:57], v[22:23] op_sel_hi:[0,1,1]
	s_waitcnt lgkmcnt(0)
	v_pk_fma_f32 v[76:77], v[92:93], v[48:49], v[76:77] op_sel_hi:[0,1,1]
	v_pk_fma_f32 v[22:23], v[26:27], v[62:63], v[22:23] op_sel:[1,0,0]
	v_pk_fma_f32 v[26:27], v[30:31], v[50:51], v[76:77] op_sel:[1,0,0]
	v_pk_fma_f32 v[22:23], v[38:39], v[42:43], v[22:23] op_sel:[1,0,0]
	v_pk_fma_f32 v[26:27], v[92:93], v[34:35], v[26:27] op_sel:[1,0,0]
	v_pk_fma_f32 v[22:23], v[28:29], v[58:59], v[22:23] op_sel_hi:[0,1,1]
	v_pk_fma_f32 v[26:27], v[32:33], v[54:55], v[26:27] op_sel_hi:[0,1,1]
	v_pk_fma_f32 v[22:23], v[40:41], v[46:47], v[22:23] op_sel_hi:[0,1,1]
	v_pk_fma_f32 v[26:27], v[94:95], v[84:85], v[26:27] op_sel_hi:[0,1,1]
	v_pk_fma_f32 v[22:23], v[28:29], v[60:61], v[22:23] op_sel:[1,0,0]
	v_pk_fma_f32 v[26:27], v[32:33], v[52:53], v[26:27] op_sel:[1,0,0]
	v_pk_fma_f32 v[22:23], v[40:41], v[44:45], v[22:23] op_sel:[1,0,0]
	v_pk_fma_f32 v[26:27], v[94:95], v[36:37], v[26:27] op_sel:[1,0,0]
	v_pk_mul_f32 v[28:29], v[80:81], v[18:19] op_sel:[0,1] op_sel_hi:[1,0]
	v_pk_add_f32 v[22:23], v[22:23], v[26:27]
	v_pk_fma_f32 v[26:27], v[78:79], v[18:19], v[28:29] neg_lo:[0,0,1] neg_hi:[0,0,1]
	v_pk_fma_f32 v[18:19], v[78:79], v[18:19], v[28:29]
	s_nop 0
	v_mov_b32_e32 v27, v19
	v_pk_add_f32 v[18:19], v[26:27], v[22:23]
	s_nop 0
	v_cvt_pk_bf16_f32 v22, v18, s0
	ds_write_b16 v16, v22 offset:1088
	v_cvt_pk_bf16_f32 v22, v19, s0
	ds_write_b16 v16, v22 offset:1216
	ds_read_b128 v[26:29], v17 offset:320
	ds_read_b128 v[30:33], v17 offset:336
	ds_read_b128 v[38:41], v17 offset:352
	ds_read_b128 v[92:95], v17 offset:368
	s_waitcnt lgkmcnt(0)
	v_pk_fma_f32 v[22:23], v[26:27], v[82:83], 0 op_sel_hi:[0,1,0]
	s_waitcnt lgkmcnt(2)
	v_pk_fma_f32 v[76:77], v[30:31], v[64:65], 0 op_sel_hi:[0,1,0]
	s_waitcnt lgkmcnt(1)
	v_pk_fma_f32 v[22:23], v[38:39], v[56:57], v[22:23] op_sel_hi:[0,1,1]
	s_waitcnt lgkmcnt(0)
	v_pk_fma_f32 v[76:77], v[92:93], v[48:49], v[76:77] op_sel_hi:[0,1,1]
	v_pk_fma_f32 v[22:23], v[26:27], v[62:63], v[22:23] op_sel:[1,0,0]
	v_pk_fma_f32 v[26:27], v[30:31], v[50:51], v[76:77] op_sel:[1,0,0]
	v_pk_fma_f32 v[22:23], v[38:39], v[42:43], v[22:23] op_sel:[1,0,0]
	v_pk_fma_f32 v[26:27], v[92:93], v[34:35], v[26:27] op_sel:[1,0,0]
	v_pk_fma_f32 v[22:23], v[28:29], v[58:59], v[22:23] op_sel_hi:[0,1,1]
	v_pk_fma_f32 v[26:27], v[32:33], v[54:55], v[26:27] op_sel_hi:[0,1,1]
	v_pk_fma_f32 v[22:23], v[40:41], v[46:47], v[22:23] op_sel_hi:[0,1,1]
	v_pk_fma_f32 v[26:27], v[94:95], v[84:85], v[26:27] op_sel_hi:[0,1,1]
	v_pk_fma_f32 v[22:23], v[28:29], v[60:61], v[22:23] op_sel:[1,0,0]
	v_pk_fma_f32 v[26:27], v[32:33], v[52:53], v[26:27] op_sel:[1,0,0]
	v_pk_fma_f32 v[22:23], v[40:41], v[44:45], v[22:23] op_sel:[1,0,0]
	v_pk_fma_f32 v[26:27], v[94:95], v[36:37], v[26:27] op_sel:[1,0,0]
	v_pk_mul_f32 v[28:29], v[80:81], v[18:19] op_sel:[0,1] op_sel_hi:[1,0]
	v_pk_add_f32 v[22:23], v[22:23], v[26:27]
	v_pk_fma_f32 v[26:27], v[78:79], v[18:19], v[28:29] neg_lo:[0,0,1] neg_hi:[0,0,1]
	v_pk_fma_f32 v[18:19], v[78:79], v[18:19], v[28:29]
	s_nop 0
	v_mov_b32_e32 v27, v19
	v_pk_add_f32 v[18:19], v[26:27], v[22:23]
	s_nop 0
	v_cvt_pk_bf16_f32 v22, v18, s0
	ds_write_b16 v16, v22 offset:1360
	v_cvt_pk_bf16_f32 v22, v19, s0
	ds_write_b16 v16, v22 offset:1488
	ds_read_b128 v[26:29], v17 offset:384
	ds_read_b128 v[30:33], v17 offset:400
	ds_read_b128 v[38:41], v17 offset:416
	ds_read_b128 v[92:95], v17 offset:432
	s_waitcnt lgkmcnt(0)
	v_pk_fma_f32 v[22:23], v[26:27], v[82:83], 0 op_sel_hi:[0,1,0]
	s_waitcnt lgkmcnt(2)
	v_pk_fma_f32 v[76:77], v[30:31], v[64:65], 0 op_sel_hi:[0,1,0]
	s_waitcnt lgkmcnt(1)
	v_pk_fma_f32 v[22:23], v[38:39], v[56:57], v[22:23] op_sel_hi:[0,1,1]
	s_waitcnt lgkmcnt(0)
	v_pk_fma_f32 v[76:77], v[92:93], v[48:49], v[76:77] op_sel_hi:[0,1,1]
	v_pk_fma_f32 v[22:23], v[26:27], v[62:63], v[22:23] op_sel:[1,0,0]
	v_pk_fma_f32 v[26:27], v[30:31], v[50:51], v[76:77] op_sel:[1,0,0]
	v_pk_fma_f32 v[22:23], v[38:39], v[42:43], v[22:23] op_sel:[1,0,0]
	v_pk_fma_f32 v[26:27], v[92:93], v[34:35], v[26:27] op_sel:[1,0,0]
	v_pk_fma_f32 v[22:23], v[28:29], v[58:59], v[22:23] op_sel_hi:[0,1,1]
	v_pk_fma_f32 v[26:27], v[32:33], v[54:55], v[26:27] op_sel_hi:[0,1,1]
	v_pk_fma_f32 v[22:23], v[40:41], v[46:47], v[22:23] op_sel_hi:[0,1,1]
	v_pk_fma_f32 v[26:27], v[94:95], v[84:85], v[26:27] op_sel_hi:[0,1,1]
	v_pk_fma_f32 v[22:23], v[28:29], v[60:61], v[22:23] op_sel:[1,0,0]
	v_pk_fma_f32 v[26:27], v[32:33], v[52:53], v[26:27] op_sel:[1,0,0]
	v_pk_fma_f32 v[22:23], v[40:41], v[44:45], v[22:23] op_sel:[1,0,0]
	v_pk_fma_f32 v[26:27], v[94:95], v[36:37], v[26:27] op_sel:[1,0,0]
	v_pk_mul_f32 v[28:29], v[80:81], v[18:19] op_sel:[0,1] op_sel_hi:[1,0]
	v_pk_add_f32 v[22:23], v[22:23], v[26:27]
	v_pk_fma_f32 v[26:27], v[78:79], v[18:19], v[28:29] neg_lo:[0,0,1] neg_hi:[0,0,1]
	v_pk_fma_f32 v[18:19], v[78:79], v[18:19], v[28:29]
	s_nop 0
	v_mov_b32_e32 v27, v19
	v_pk_add_f32 v[18:19], v[26:27], v[22:23]
	s_nop 0
	v_cvt_pk_bf16_f32 v22, v18, s0
	ds_write_b16 v16, v22 offset:1632
	v_cvt_pk_bf16_f32 v22, v19, s0
	ds_write_b16 v16, v22 offset:1760
	ds_read_b128 v[26:29], v17 offset:448
	ds_read_b128 v[30:33], v17 offset:464
	ds_read_b128 v[38:41], v17 offset:480
	ds_read_b128 v[92:95], v17 offset:496
	s_waitcnt lgkmcnt(0)
	v_pk_fma_f32 v[22:23], v[26:27], v[82:83], 0 op_sel_hi:[0,1,0]
	s_waitcnt lgkmcnt(2)
	v_pk_fma_f32 v[76:77], v[30:31], v[64:65], 0 op_sel_hi:[0,1,0]
	s_waitcnt lgkmcnt(1)
	v_pk_fma_f32 v[22:23], v[38:39], v[56:57], v[22:23] op_sel_hi:[0,1,1]
	s_waitcnt lgkmcnt(0)
	v_pk_fma_f32 v[76:77], v[92:93], v[48:49], v[76:77] op_sel_hi:[0,1,1]
	v_pk_fma_f32 v[22:23], v[26:27], v[62:63], v[22:23] op_sel:[1,0,0]
	v_pk_fma_f32 v[26:27], v[30:31], v[50:51], v[76:77] op_sel:[1,0,0]
	v_pk_fma_f32 v[22:23], v[38:39], v[42:43], v[22:23] op_sel:[1,0,0]
	v_pk_fma_f32 v[26:27], v[92:93], v[34:35], v[26:27] op_sel:[1,0,0]
	v_pk_fma_f32 v[22:23], v[28:29], v[58:59], v[22:23] op_sel_hi:[0,1,1]
	v_pk_fma_f32 v[26:27], v[32:33], v[54:55], v[26:27] op_sel_hi:[0,1,1]
	v_pk_fma_f32 v[22:23], v[40:41], v[46:47], v[22:23] op_sel_hi:[0,1,1]
	v_pk_fma_f32 v[26:27], v[94:95], v[84:85], v[26:27] op_sel_hi:[0,1,1]
	v_pk_fma_f32 v[22:23], v[28:29], v[60:61], v[22:23] op_sel:[1,0,0]
	v_pk_fma_f32 v[26:27], v[32:33], v[52:53], v[26:27] op_sel:[1,0,0]
	v_pk_fma_f32 v[22:23], v[40:41], v[44:45], v[22:23] op_sel:[1,0,0]
	v_pk_fma_f32 v[26:27], v[94:95], v[36:37], v[26:27] op_sel:[1,0,0]
	v_pk_mul_f32 v[28:29], v[80:81], v[18:19] op_sel:[0,1] op_sel_hi:[1,0]
	v_pk_add_f32 v[22:23], v[22:23], v[26:27]
	v_pk_fma_f32 v[26:27], v[78:79], v[18:19], v[28:29] neg_lo:[0,0,1] neg_hi:[0,0,1]
	v_pk_fma_f32 v[18:19], v[78:79], v[18:19], v[28:29]
	s_nop 0
	v_mov_b32_e32 v27, v19
	v_pk_add_f32 v[76:77], v[26:27], v[22:23]
	s_nop 0
	v_cvt_pk_bf16_f32 v17, v76, s0
	ds_write_b16 v16, v17 offset:1904
	v_cvt_pk_bf16_f32 v17, v77, s0
	ds_write_b16 v16, v17 offset:2032
	v_add_u32_e32 v16, 0x880, v16
	s_cbranch_scc0 .LBB0_208
	ds_read_b128 v[16:19], v90
	ds_read_b128 v[26:29], v90 offset:64
	v_lshl_or_b32 v25, s6, 4, v87
	v_or_b32_e32 v22, s8, v25
	v_mov_b32_e32 v23, s9
	s_add_i32 s6, s6, 1
	s_addk_i32 s10, 0x400
	s_cmp_eq_u32 s6, 4
	s_waitcnt lgkmcnt(0)
	v_mfma_f32_16x16x32_bf16 v[16:19], v[16:19], v[0:3], 0
	s_waitcnt lgkmcnt(0)
	v_mfma_f32_16x16x32_bf16 v[16:19], v[26:29], v[4:7], v[16:19]
	ds_read_b128 v[26:29], v90 offset:128
	s_waitcnt lgkmcnt(0)
	v_mfma_f32_16x16x32_bf16 v[16:19], v[26:29], v[8:11], v[16:19]
	ds_read_b128 v[26:29], v90 offset:192
	s_waitcnt lgkmcnt(0)
	v_mfma_f32_16x16x32_bf16 v[16:19], v[26:29], v[12:15], v[16:19]
	v_lshl_add_u32 v26, v25, 6, v88
	ds_read_b32 v26, v26 offset:34816
	s_waitcnt lgkmcnt(0)
	s_nop 4
	v_fma_f32 v16, v24, v26, v16
	v_mul_f32_e32 v26, 0x3d372713, v16
	v_mul_f32_e32 v26, v16, v26
	v_fma_f32 v26, v16, v26, v16
	v_mul_f32_e32 v26, 0x3f4c422a, v26
	v_mul_f32_e32 v26, -2.0, v26
	v_mul_f32_e32 v26, 0x3fb8aa3b, v26
	v_exp_f32_e32 v26, v26
	s_nop 0
	v_add_f32_e32 v26, 1.0, v26
	v_rcp_f32_e32 v26, v26
	s_nop 0
	v_mul_f32_e32 v16, v16, v26
	v_lshlrev_b64 v[26:27], 10, v[22:23]
	v_cvt_pk_bf16_f32 v16, v16, s0
	v_lshl_add_u64 v[26:27], v[20:21], 0, v[26:27]
	flat_store_short v[26:27], v16
	v_or_b32_e32 v16, 1, v25
	v_or_b32_e32 v22, s8, v16
	v_lshl_add_u32 v16, v16, 6, v88
	ds_read_b32 v16, v16 offset:34816
	s_waitcnt lgkmcnt(0)
	v_fma_f32 v16, v24, v16, v17
	v_mul_f32_e32 v17, 0x3d372713, v16
	v_mul_f32_e32 v17, v16, v17
	v_fma_f32 v17, v16, v17, v16
	v_mul_f32_e32 v17, 0x3f4c422a, v17
	v_mul_f32_e32 v17, -2.0, v17
	v_mul_f32_e32 v17, 0x3fb8aa3b, v17
	v_exp_f32_e32 v17, v17
	s_nop 0
	v_add_f32_e32 v17, 1.0, v17
	v_rcp_f32_e32 v17, v17
	s_nop 0
	v_mul_f32_e32 v16, v16, v17
	v_cvt_pk_bf16_f32 v26, v16, s0
	v_lshlrev_b64 v[16:17], 10, v[22:23]
	v_lshl_add_u64 v[16:17], v[20:21], 0, v[16:17]
	flat_store_short v[16:17], v26
	v_or_b32_e32 v16, 2, v25
	v_or_b32_e32 v22, s8, v16
	v_lshl_add_u32 v16, v16, 6, v88
	ds_read_b32 v16, v16 offset:34816
	s_waitcnt lgkmcnt(0)
	v_fma_f32 v16, v24, v16, v18
	v_mul_f32_e32 v17, 0x3d372713, v16
	v_mul_f32_e32 v17, v16, v17
	v_fma_f32 v17, v16, v17, v16
	v_mul_f32_e32 v17, 0x3f4c422a, v17
	v_mul_f32_e32 v17, -2.0, v17
	v_mul_f32_e32 v17, 0x3fb8aa3b, v17
	v_exp_f32_e32 v17, v17
	s_nop 0
	v_add_f32_e32 v17, 1.0, v17
	v_rcp_f32_e32 v17, v17
	s_nop 0
	v_mul_f32_e32 v16, v16, v17
	v_cvt_pk_bf16_f32 v18, v16, s0
	v_lshlrev_b64 v[16:17], 10, v[22:23]
	v_lshl_add_u64 v[16:17], v[20:21], 0, v[16:17]
	flat_store_short v[16:17], v18
	v_or_b32_e32 v16, 3, v25
	v_or_b32_e32 v22, s8, v16
	v_lshl_add_u32 v16, v16, 6, v88
	ds_read_b32 v16, v16 offset:34816
	s_waitcnt lgkmcnt(0)
	v_fmac_f32_e32 v19, v24, v16
	v_mul_f32_e32 v16, 0x3d372713, v19
	v_mul_f32_e32 v16, v19, v16
	v_fma_f32 v16, v19, v16, v19
	v_mul_f32_e32 v16, 0x3f4c422a, v16
	v_mul_f32_e32 v16, -2.0, v16
	v_mul_f32_e32 v16, 0x3fb8aa3b, v16
	v_exp_f32_e32 v16, v16
	s_nop 0
	v_add_f32_e32 v16, 1.0, v16
	v_rcp_f32_e32 v16, v16
	s_nop 0
	v_mul_f32_e32 v16, v19, v16
	v_cvt_pk_bf16_f32 v18, v16, s0
	v_lshlrev_b64 v[16:17], 10, v[22:23]
	v_lshl_add_u64 v[16:17], v[20:21], 0, v[16:17]
	flat_store_short v[16:17], v18
	s_cbranch_scc0 .LBB0_207
	s_mov_b32 s12, 0
	s_mov_b32 s6, s23
	s_branch .LBB0_162

.LBB0_233:
	s_add_i32 s6, s13, s1
	v_mov_b32_e32 v51, s6
	ds_read_b128 v[0:3], v51
	ds_read_b128 v[4:7], v51 offset:16
	ds_read_b128 v[52:55], v51 offset:32
	ds_read_b128 v[56:59], v51 offset:48
	s_addk_i32 s1, 0x200
	s_waitcnt lgkmcnt(3)
	v_pk_fma_f32 v[60:61], v[0:1], v[18:19], 0 op_sel_hi:[0,1,0]
	s_waitcnt lgkmcnt(2)
	v_pk_fma_f32 v[62:63], v[4:5], v[26:27], 0 op_sel_hi:[0,1,0]
	s_waitcnt lgkmcnt(1)
	v_pk_fma_f32 v[60:61], v[52:53], v[34:35], v[60:61] op_sel_hi:[0,1,1]
	s_waitcnt lgkmcnt(0)
	v_pk_fma_f32 v[62:63], v[56:57], v[42:43], v[62:63] op_sel_hi:[0,1,1]
	v_pk_fma_f32 v[0:1], v[0:1], v[20:21], v[60:61] op_sel:[1,0,0]
	v_pk_fma_f32 v[4:5], v[4:5], v[28:29], v[62:63] op_sel:[1,0,0]
	v_pk_fma_f32 v[0:1], v[52:53], v[36:37], v[0:1] op_sel:[1,0,0]
	v_pk_fma_f32 v[4:5], v[56:57], v[44:45], v[4:5] op_sel:[1,0,0]
	v_pk_fma_f32 v[0:1], v[2:3], v[22:23], v[0:1] op_sel_hi:[0,1,1]
	v_pk_fma_f32 v[4:5], v[6:7], v[30:31], v[4:5] op_sel_hi:[0,1,1]
	v_pk_fma_f32 v[0:1], v[54:55], v[38:39], v[0:1] op_sel_hi:[0,1,1]
	v_pk_fma_f32 v[4:5], v[58:59], v[46:47], v[4:5] op_sel_hi:[0,1,1]
	v_pk_fma_f32 v[0:1], v[2:3], v[24:25], v[0:1] op_sel:[1,0,0]
	v_mov_b32_e32 v2, v7
	v_pk_fma_f32 v[2:3], v[2:3], v[32:33], v[4:5] op_sel_hi:[0,1,1]
	v_pk_fma_f32 v[0:1], v[54:55], v[40:41], v[0:1] op_sel:[1,0,0]
	v_pk_fma_f32 v[2:3], v[58:59], v[48:49], v[2:3] op_sel:[1,0,0]
	v_pk_mul_f32 v[4:5], v[14:15], v[16:17] op_sel:[0,1] op_sel_hi:[1,0]
	v_pk_add_f32 v[0:1], v[2:3], v[0:1]
	v_pk_fma_f32 v[2:3], v[12:13], v[16:17], v[4:5] neg_lo:[0,0,1] neg_hi:[0,0,1]
	v_pk_fma_f32 v[4:5], v[12:13], v[16:17], v[4:5]
	s_cmpk_eq_i32 s1, 0x1000
	v_mov_b32_e32 v3, v5
	v_pk_add_f32 v[16:17], v[2:3], v[0:1]
	ds_read_b128 v[0:3], v51 offset:64
	ds_read_b128 v[4:7], v51 offset:80
	ds_read_b128 v[52:55], v51 offset:96
	ds_read_b128 v[56:59], v51 offset:112
	s_waitcnt lgkmcnt(3)
	v_pk_fma_f32 v[60:61], v[0:1], v[18:19], 0 op_sel_hi:[0,1,0]
	s_waitcnt lgkmcnt(2)
	v_pk_fma_f32 v[62:63], v[4:5], v[26:27], 0 op_sel_hi:[0,1,0]
	s_waitcnt lgkmcnt(1)
	v_pk_fma_f32 v[60:61], v[52:53], v[34:35], v[60:61] op_sel_hi:[0,1,1]
	s_waitcnt lgkmcnt(0)
	v_pk_fma_f32 v[62:63], v[56:57], v[42:43], v[62:63] op_sel_hi:[0,1,1]
	v_pk_fma_f32 v[0:1], v[0:1], v[20:21], v[60:61] op_sel:[1,0,0]
	v_pk_fma_f32 v[4:5], v[4:5], v[28:29], v[62:63] op_sel:[1,0,0]
	v_pk_fma_f32 v[0:1], v[52:53], v[36:37], v[0:1] op_sel:[1,0,0]
	v_pk_fma_f32 v[4:5], v[56:57], v[44:45], v[4:5] op_sel:[1,0,0]
	v_pk_fma_f32 v[0:1], v[2:3], v[22:23], v[0:1] op_sel_hi:[0,1,1]
	v_pk_fma_f32 v[4:5], v[6:7], v[30:31], v[4:5] op_sel_hi:[0,1,1]
	v_pk_fma_f32 v[0:1], v[54:55], v[38:39], v[0:1] op_sel_hi:[0,1,1]
	v_pk_fma_f32 v[4:5], v[58:59], v[46:47], v[4:5] op_sel_hi:[0,1,1]
	v_pk_fma_f32 v[0:1], v[2:3], v[24:25], v[0:1] op_sel:[1,0,0]
	v_mov_b32_e32 v2, v7
	v_pk_fma_f32 v[2:3], v[2:3], v[32:33], v[4:5] op_sel_hi:[0,1,1]
	v_pk_fma_f32 v[0:1], v[54:55], v[40:41], v[0:1] op_sel:[1,0,0]
	v_pk_fma_f32 v[2:3], v[58:59], v[48:49], v[2:3] op_sel:[1,0,0]
	v_pk_mul_f32 v[4:5], v[14:15], v[16:17] op_sel:[0,1] op_sel_hi:[1,0]
	v_pk_add_f32 v[0:1], v[2:3], v[0:1]
	v_pk_fma_f32 v[2:3], v[12:13], v[16:17], v[4:5] neg_lo:[0,0,1] neg_hi:[0,0,1]
	v_pk_fma_f32 v[4:5], v[12:13], v[16:17], v[4:5]
	s_nop 0
	v_mov_b32_e32 v3, v5
	v_pk_add_f32 v[16:17], v[2:3], v[0:1]
	ds_read_b128 v[0:3], v51 offset:128
	ds_read_b128 v[4:7], v51 offset:144
	ds_read_b128 v[52:55], v51 offset:160
	ds_read_b128 v[56:59], v51 offset:176
	s_waitcnt lgkmcnt(3)
	v_pk_fma_f32 v[60:61], v[0:1], v[18:19], 0 op_sel_hi:[0,1,0]
	s_waitcnt lgkmcnt(2)
	v_pk_fma_f32 v[62:63], v[4:5], v[26:27], 0 op_sel_hi:[0,1,0]
	s_waitcnt lgkmcnt(1)
	v_pk_fma_f32 v[60:61], v[52:53], v[34:35], v[60:61] op_sel_hi:[0,1,1]
	s_waitcnt lgkmcnt(0)
	v_pk_fma_f32 v[62:63], v[56:57], v[42:43], v[62:63] op_sel_hi:[0,1,1]
	v_pk_fma_f32 v[0:1], v[0:1], v[20:21], v[60:61] op_sel:[1,0,0]
	v_pk_fma_f32 v[4:5], v[4:5], v[28:29], v[62:63] op_sel:[1,0,0]
	v_pk_fma_f32 v[0:1], v[52:53], v[36:37], v[0:1] op_sel:[1,0,0]
	v_pk_fma_f32 v[4:5], v[56:57], v[44:45], v[4:5] op_sel:[1,0,0]
	v_pk_fma_f32 v[0:1], v[2:3], v[22:23], v[0:1] op_sel_hi:[0,1,1]
	v_pk_fma_f32 v[4:5], v[6:7], v[30:31], v[4:5] op_sel_hi:[0,1,1]
	v_pk_fma_f32 v[0:1], v[54:55], v[38:39], v[0:1] op_sel_hi:[0,1,1]
	v_pk_fma_f32 v[4:5], v[58:59], v[46:47], v[4:5] op_sel_hi:[0,1,1]
	v_pk_fma_f32 v[0:1], v[2:3], v[24:25], v[0:1] op_sel:[1,0,0]
	v_mov_b32_e32 v2, v7
	v_pk_fma_f32 v[2:3], v[2:3], v[32:33], v[4:5] op_sel_hi:[0,1,1]
	v_pk_fma_f32 v[0:1], v[54:55], v[40:41], v[0:1] op_sel:[1,0,0]
	v_pk_fma_f32 v[2:3], v[58:59], v[48:49], v[2:3] op_sel:[1,0,0]
	v_pk_mul_f32 v[4:5], v[14:15], v[16:17] op_sel:[0,1] op_sel_hi:[1,0]
	v_pk_add_f32 v[0:1], v[2:3], v[0:1]
	v_pk_fma_f32 v[2:3], v[12:13], v[16:17], v[4:5] neg_lo:[0,0,1] neg_hi:[0,0,1]
	v_pk_fma_f32 v[4:5], v[12:13], v[16:17], v[4:5]
	s_nop 0
	v_mov_b32_e32 v3, v5
	v_pk_add_f32 v[16:17], v[2:3], v[0:1]
	ds_read_b128 v[0:3], v51 offset:192
	ds_read_b128 v[4:7], v51 offset:208
	ds_read_b128 v[52:55], v51 offset:224
	ds_read_b128 v[56:59], v51 offset:240
	s_waitcnt lgkmcnt(3)
	v_pk_fma_f32 v[60:61], v[0:1], v[18:19], 0 op_sel_hi:[0,1,0]
	s_waitcnt lgkmcnt(2)
	v_pk_fma_f32 v[62:63], v[4:5], v[26:27], 0 op_sel_hi:[0,1,0]
	s_waitcnt lgkmcnt(1)
	v_pk_fma_f32 v[60:61], v[52:53], v[34:35], v[60:61] op_sel_hi:[0,1,1]
	s_waitcnt lgkmcnt(0)
	v_pk_fma_f32 v[62:63], v[56:57], v[42:43], v[62:63] op_sel_hi:[0,1,1]
	v_pk_fma_f32 v[0:1], v[0:1], v[20:21], v[60:61] op_sel:[1,0,0]
	v_pk_fma_f32 v[4:5], v[4:5], v[28:29], v[62:63] op_sel:[1,0,0]
	v_pk_fma_f32 v[0:1], v[52:53], v[36:37], v[0:1] op_sel:[1,0,0]
	v_pk_fma_f32 v[4:5], v[56:57], v[44:45], v[4:5] op_sel:[1,0,0]
	v_pk_fma_f32 v[0:1], v[2:3], v[22:23], v[0:1] op_sel_hi:[0,1,1]
	v_pk_fma_f32 v[4:5], v[6:7], v[30:31], v[4:5] op_sel_hi:[0,1,1]
	v_pk_fma_f32 v[0:1], v[54:55], v[38:39], v[0:1] op_sel_hi:[0,1,1]
	v_pk_fma_f32 v[4:5], v[58:59], v[46:47], v[4:5] op_sel_hi:[0,1,1]
	v_pk_fma_f32 v[0:1], v[2:3], v[24:25], v[0:1] op_sel:[1,0,0]
	v_mov_b32_e32 v2, v7
	v_pk_fma_f32 v[2:3], v[2:3], v[32:33], v[4:5] op_sel_hi:[0,1,1]
	v_pk_fma_f32 v[0:1], v[54:55], v[40:41], v[0:1] op_sel:[1,0,0]
	v_pk_fma_f32 v[2:3], v[58:59], v[48:49], v[2:3] op_sel:[1,0,0]
	v_pk_mul_f32 v[4:5], v[14:15], v[16:17] op_sel:[0,1] op_sel_hi:[1,0]
	v_pk_add_f32 v[0:1], v[2:3], v[0:1]
	v_pk_fma_f32 v[2:3], v[12:13], v[16:17], v[4:5] neg_lo:[0,0,1] neg_hi:[0,0,1]
	v_pk_fma_f32 v[4:5], v[12:13], v[16:17], v[4:5]
	s_nop 0
	v_mov_b32_e32 v3, v5
	v_pk_add_f32 v[16:17], v[2:3], v[0:1]
	ds_read_b128 v[0:3], v51 offset:256
	ds_read_b128 v[4:7], v51 offset:272
	ds_read_b128 v[52:55], v51 offset:288
	ds_read_b128 v[56:59], v51 offset:304
	s_waitcnt lgkmcnt(3)
	v_pk_fma_f32 v[60:61], v[0:1], v[18:19], 0 op_sel_hi:[0,1,0]
	s_waitcnt lgkmcnt(2)
	v_pk_fma_f32 v[62:63], v[4:5], v[26:27], 0 op_sel_hi:[0,1,0]
	s_waitcnt lgkmcnt(1)
	v_pk_fma_f32 v[60:61], v[52:53], v[34:35], v[60:61] op_sel_hi:[0,1,1]
	s_waitcnt lgkmcnt(0)
	v_pk_fma_f32 v[62:63], v[56:57], v[42:43], v[62:63] op_sel_hi:[0,1,1]
	v_pk_fma_f32 v[0:1], v[0:1], v[20:21], v[60:61] op_sel:[1,0,0]
	v_pk_fma_f32 v[4:5], v[4:5], v[28:29], v[62:63] op_sel:[1,0,0]
	v_pk_fma_f32 v[0:1], v[52:53], v[36:37], v[0:1] op_sel:[1,0,0]
	v_pk_fma_f32 v[4:5], v[56:57], v[44:45], v[4:5] op_sel:[1,0,0]
	v_pk_fma_f32 v[0:1], v[2:3], v[22:23], v[0:1] op_sel_hi:[0,1,1]
	v_pk_fma_f32 v[4:5], v[6:7], v[30:31], v[4:5] op_sel_hi:[0,1,1]
	v_pk_fma_f32 v[0:1], v[54:55], v[38:39], v[0:1] op_sel_hi:[0,1,1]
	v_pk_fma_f32 v[4:5], v[58:59], v[46:47], v[4:5] op_sel_hi:[0,1,1]
	v_pk_fma_f32 v[0:1], v[2:3], v[24:25], v[0:1] op_sel:[1,0,0]
	v_mov_b32_e32 v2, v7
	v_pk_fma_f32 v[2:3], v[2:3], v[32:33], v[4:5] op_sel_hi:[0,1,1]
	v_pk_fma_f32 v[0:1], v[54:55], v[40:41], v[0:1] op_sel:[1,0,0]
	v_pk_fma_f32 v[2:3], v[58:59], v[48:49], v[2:3] op_sel:[1,0,0]
	v_pk_mul_f32 v[4:5], v[14:15], v[16:17] op_sel:[0,1] op_sel_hi:[1,0]
	v_pk_add_f32 v[0:1], v[2:3], v[0:1]
	v_pk_fma_f32 v[2:3], v[12:13], v[16:17], v[4:5] neg_lo:[0,0,1] neg_hi:[0,0,1]
	v_pk_fma_f32 v[4:5], v[12:13], v[16:17], v[4:5]
	s_nop 0
	v_mov_b32_e32 v3, v5
	v_pk_add_f32 v[16:17], v[2:3], v[0:1]
	ds_read_b128 v[0:3], v51 offset:320
	ds_read_b128 v[4:7], v51 offset:336
	ds_read_b128 v[52:55], v51 offset:352
	ds_read_b128 v[56:59], v51 offset:368
	s_waitcnt lgkmcnt(3)
	v_pk_fma_f32 v[60:61], v[0:1], v[18:19], 0 op_sel_hi:[0,1,0]
	s_waitcnt lgkmcnt(2)
	v_pk_fma_f32 v[62:63], v[4:5], v[26:27], 0 op_sel_hi:[0,1,0]
	s_waitcnt lgkmcnt(1)
	v_pk_fma_f32 v[60:61], v[52:53], v[34:35], v[60:61] op_sel_hi:[0,1,1]
	s_waitcnt lgkmcnt(0)
	v_pk_fma_f32 v[62:63], v[56:57], v[42:43], v[62:63] op_sel_hi:[0,1,1]
	v_pk_fma_f32 v[0:1], v[0:1], v[20:21], v[60:61] op_sel:[1,0,0]
	v_pk_fma_f32 v[4:5], v[4:5], v[28:29], v[62:63] op_sel:[1,0,0]
	v_pk_fma_f32 v[0:1], v[52:53], v[36:37], v[0:1] op_sel:[1,0,0]
	v_pk_fma_f32 v[4:5], v[56:57], v[44:45], v[4:5] op_sel:[1,0,0]
	v_pk_fma_f32 v[0:1], v[2:3], v[22:23], v[0:1] op_sel_hi:[0,1,1]
	v_pk_fma_f32 v[4:5], v[6:7], v[30:31], v[4:5] op_sel_hi:[0,1,1]
	v_pk_fma_f32 v[0:1], v[54:55], v[38:39], v[0:1] op_sel_hi:[0,1,1]
	v_pk_fma_f32 v[4:5], v[58:59], v[46:47], v[4:5] op_sel_hi:[0,1,1]
	v_pk_fma_f32 v[0:1], v[2:3], v[24:25], v[0:1] op_sel:[1,0,0]
	v_mov_b32_e32 v2, v7
	v_pk_fma_f32 v[2:3], v[2:3], v[32:33], v[4:5] op_sel_hi:[0,1,1]
	v_pk_fma_f32 v[0:1], v[54:55], v[40:41], v[0:1] op_sel:[1,0,0]
	v_pk_fma_f32 v[2:3], v[58:59], v[48:49], v[2:3] op_sel:[1,0,0]
	v_pk_mul_f32 v[4:5], v[14:15], v[16:17] op_sel:[0,1] op_sel_hi:[1,0]
	v_pk_add_f32 v[0:1], v[2:3], v[0:1]
	v_pk_fma_f32 v[2:3], v[12:13], v[16:17], v[4:5] neg_lo:[0,0,1] neg_hi:[0,0,1]
	v_pk_fma_f32 v[4:5], v[12:13], v[16:17], v[4:5]
	s_nop 0
	v_mov_b32_e32 v3, v5
	v_pk_add_f32 v[16:17], v[2:3], v[0:1]
	ds_read_b128 v[0:3], v51 offset:384
	ds_read_b128 v[4:7], v51 offset:400
	ds_read_b128 v[52:55], v51 offset:416
	ds_read_b128 v[56:59], v51 offset:432
	s_waitcnt lgkmcnt(3)
	v_pk_fma_f32 v[60:61], v[0:1], v[18:19], 0 op_sel_hi:[0,1,0]
	s_waitcnt lgkmcnt(2)
	v_pk_fma_f32 v[62:63], v[4:5], v[26:27], 0 op_sel_hi:[0,1,0]
	s_waitcnt lgkmcnt(1)
	v_pk_fma_f32 v[60:61], v[52:53], v[34:35], v[60:61] op_sel_hi:[0,1,1]
	s_waitcnt lgkmcnt(0)
	v_pk_fma_f32 v[62:63], v[56:57], v[42:43], v[62:63] op_sel_hi:[0,1,1]
	v_pk_fma_f32 v[0:1], v[0:1], v[20:21], v[60:61] op_sel:[1,0,0]
	v_pk_fma_f32 v[4:5], v[4:5], v[28:29], v[62:63] op_sel:[1,0,0]
	v_pk_fma_f32 v[0:1], v[52:53], v[36:37], v[0:1] op_sel:[1,0,0]
	v_pk_fma_f32 v[4:5], v[56:57], v[44:45], v[4:5] op_sel:[1,0,0]
	v_pk_fma_f32 v[0:1], v[2:3], v[22:23], v[0:1] op_sel_hi:[0,1,1]
	v_pk_fma_f32 v[4:5], v[6:7], v[30:31], v[4:5] op_sel_hi:[0,1,1]
	v_pk_fma_f32 v[0:1], v[54:55], v[38:39], v[0:1] op_sel_hi:[0,1,1]
	v_pk_fma_f32 v[4:5], v[58:59], v[46:47], v[4:5] op_sel_hi:[0,1,1]
	v_pk_fma_f32 v[0:1], v[2:3], v[24:25], v[0:1] op_sel:[1,0,0]
	v_mov_b32_e32 v2, v7
	v_pk_fma_f32 v[2:3], v[2:3], v[32:33], v[4:5] op_sel_hi:[0,1,1]
	v_pk_fma_f32 v[0:1], v[54:55], v[40:41], v[0:1] op_sel:[1,0,0]
	v_pk_fma_f32 v[2:3], v[58:59], v[48:49], v[2:3] op_sel:[1,0,0]
	v_pk_mul_f32 v[4:5], v[14:15], v[16:17] op_sel:[0,1] op_sel_hi:[1,0]
	v_pk_add_f32 v[0:1], v[2:3], v[0:1]
	v_pk_fma_f32 v[2:3], v[12:13], v[16:17], v[4:5] neg_lo:[0,0,1] neg_hi:[0,0,1]
	v_pk_fma_f32 v[4:5], v[12:13], v[16:17], v[4:5]
	s_nop 0
	v_mov_b32_e32 v3, v5
	v_pk_add_f32 v[16:17], v[2:3], v[0:1]
	ds_read_b128 v[0:3], v51 offset:448
	ds_read_b128 v[4:7], v51 offset:464
	ds_read_b128 v[52:55], v51 offset:480
	ds_read_b128 v[56:59], v51 offset:496
	s_waitcnt lgkmcnt(3)
	v_pk_fma_f32 v[60:61], v[0:1], v[18:19], 0 op_sel_hi:[0,1,0]
	s_waitcnt lgkmcnt(2)
	v_pk_fma_f32 v[62:63], v[4:5], v[26:27], 0 op_sel_hi:[0,1,0]
	s_waitcnt lgkmcnt(1)
	v_pk_fma_f32 v[60:61], v[52:53], v[34:35], v[60:61] op_sel_hi:[0,1,1]
	s_waitcnt lgkmcnt(0)
	v_pk_fma_f32 v[62:63], v[56:57], v[42:43], v[62:63] op_sel_hi:[0,1,1]
	v_pk_fma_f32 v[0:1], v[0:1], v[20:21], v[60:61] op_sel:[1,0,0]
	v_pk_fma_f32 v[4:5], v[4:5], v[28:29], v[62:63] op_sel:[1,0,0]
	v_pk_fma_f32 v[0:1], v[52:53], v[36:37], v[0:1] op_sel:[1,0,0]
	v_pk_fma_f32 v[4:5], v[56:57], v[44:45], v[4:5] op_sel:[1,0,0]
	v_pk_fma_f32 v[0:1], v[2:3], v[22:23], v[0:1] op_sel_hi:[0,1,1]
	v_pk_fma_f32 v[4:5], v[6:7], v[30:31], v[4:5] op_sel_hi:[0,1,1]
	v_pk_fma_f32 v[0:1], v[54:55], v[38:39], v[0:1] op_sel_hi:[0,1,1]
	v_pk_fma_f32 v[4:5], v[58:59], v[46:47], v[4:5] op_sel_hi:[0,1,1]
	v_pk_fma_f32 v[0:1], v[2:3], v[24:25], v[0:1] op_sel:[1,0,0]
	v_mov_b32_e32 v2, v7
	v_pk_fma_f32 v[2:3], v[2:3], v[32:33], v[4:5] op_sel_hi:[0,1,1]
	v_pk_fma_f32 v[0:1], v[54:55], v[40:41], v[0:1] op_sel:[1,0,0]
	v_pk_fma_f32 v[2:3], v[58:59], v[48:49], v[2:3] op_sel:[1,0,0]
	v_pk_mul_f32 v[4:5], v[14:15], v[16:17] op_sel:[0,1] op_sel_hi:[1,0]
	v_pk_add_f32 v[0:1], v[2:3], v[0:1]
	v_pk_fma_f32 v[2:3], v[12:13], v[16:17], v[4:5] neg_lo:[0,0,1] neg_hi:[0,0,1]
	v_pk_fma_f32 v[4:5], v[12:13], v[16:17], v[4:5]
	s_nop 0
	v_mov_b32_e32 v3, v5
	v_pk_add_f32 v[16:17], v[2:3], v[0:1]
	s_cbranch_scc0 .LBB0_233
	s_ashr_i32 s1, s0, 31
	s_lshl_b64 s[8:9], s[0:1], 9
	s_add_i32 s0, s0, s36
	v_lshl_add_u64 v[0:1], v[8:9], 0, s[8:9]
	s_cmpk_gt_i32 s0, 0x1fff
	flat_store_dwordx2 v[0:1], v[16:17]
	s_cbranch_scc0 .LBB0_222
